# prologue de-serialisation: workgroup 0's barrier-word init no longer waits after the ready-flag store and the L2 invalidate
# speedup vs baseline: 1.0109x; 1.0109x over previous
; #define LAS __attribute__((address_space(3)))
; __device__ __forceinline__ CArgsP get_args() { CArgsP p = (CArgsP)__builtin_amdgcn_kernarg_segment_ptr(); asm volatile("" : "+s"(p)); return p; }
; __global__ void __launch_bounds__(512, 2) mega_fwd(Args a_unused) {
;     ...
;     if (tid < 64) ((LAS unsigned*)(lds + 131072))[tid] = 0u;
;     __syncthreads();
;     { CArgsP a = get_args(); phase0(a, lds, wave, lane);
;       if (bx == 0) { unsigned* bw = (unsigned*)(a->ws + WS_BAR); for (int i = tid; i < (int)(BAR_BYTES / 4); i += 512) bw[i] = 0u; } }
_Z8mega_fwd4Args:
	s_load_dwordx2 s[60:61], s[0:1], 0x100
	s_load_dword s78, s[0:1], 0x108
	s_mov_b64 s[92:93], s[0:1]
	v_and_b32_e32 v164, 0x3ff, v0
	s_add_u32 s10, s92, 0x100
	v_cmp_lt_u32_e64 s[0:1], 63, v164
	s_addc_u32 s11, s93, 0
	v_readfirstlane_b32 s44, v164
	v_writelane_b32 v250, s0, 0
	v_cmp_gt_u32_e64 s[8:9], 64, v164
	v_lshl_add_u32 v149, v164, 2, 0
	v_writelane_b32 v250, s1, 1
	s_and_saveexec_b64 s[4:5], s[8:9]
	v_lshl_add_u32 v1, v164, 2, 0
	v_add_u32_e32 v1, 0x20000, v1
	v_mov_b32_e32 v2, 0
	ds_write_b32 v1, v2
	s_or_b64 exec, exec, s[4:5]
	s_mov_b64 s[18:19], s[92:93]
	s_waitcnt lgkmcnt(0)
	s_barrier
	s_cmp_lg_u32 s2, 0
	s_cbranch_scc1 .Lz_done
	s_load_dwordx2 s[16:17], s[92:93], 0xf8
	v_lshlrev_b32_e32 v1, 2, v164
	v_mov_b32_e32 v2, 0
	s_waitcnt lgkmcnt(0)
	s_add_u32 s16, s16, 0x80000
	s_addc_u32 s17, s17, 0
	global_store_dword v1, v2, s[16:17]
	global_store_dword v1, v2, s[16:17] offset:2048
	v_add_u32_e32 v1, 0x1000, v1
	global_store_dword v1, v2, s[16:17]
	global_store_dword v1, v2, s[16:17] offset:2048
	v_add_u32_e32 v1, 0x1000, v1
	global_store_dword v1, v2, s[16:17]
	global_store_dword v1, v2, s[16:17] offset:2048
	v_add_u32_e32 v1, 0x1000, v1
	global_store_dword v1, v2, s[16:17]
	global_store_dword v1, v2, s[16:17] offset:2048
	s_waitcnt vmcnt(0)
	s_barrier
	s_cmp_lg_u32 s44, 0
	s_cbranch_scc1 .Lz_done
	buffer_wbl2 sc1
	s_waitcnt vmcnt(0)
	v_mov_b32_e32 v1, 0x3e80
	v_mov_b32_e32 v2, 0x5a17c0de
	global_store_dword v1, v2, s[16:17] sc0 sc1
	buffer_inv sc1
